# P5 rotation table balanced per workgroup (max 3 K/V tiles each, none in last round) + P2/P10 spread
# baseline (speedup 1.0000x reference)
.LBB0_510:
	s_ashr_i32 s4, s6, 3
	s_add_i32 s4, s8, s4
	s_mul_hi_i32 s5, s4, 0x3e0f83e1
	s_lshr_b32 s6, s5, 31
	s_ashr_i32 s5, s5, 6
	s_add_i32 s5, s5, s6
	s_lshl_b32 s6, s5, 3
	s_sub_i32 s7, 0x44, s6
	s_mulk_i32 s5, 0x108
	s_min_u32 s7, s7, 8
	s_sub_i32 s9, s4, s5
	s_sext_i32_i16 s4, s9
	v_cvt_f32_ubyte0_e32 v1, s7
	v_cvt_f32_i32_e32 v0, s4
	v_rcp_iflag_f32_e32 v2, v1
	s_ashr_i32 s4, s4, 30
	s_or_b32 s8, s4, 1
	v_mul_f32_e32 v2, v0, v2
	v_trunc_f32_e32 v2, v2
	v_fma_f32 v0, -v2, v1, v0
	v_cvt_i32_f32_e32 v2, v2
	v_cmp_ge_f32_e64 s[4:5], |v0|, v1
	s_and_b64 s[4:5], s[4:5], exec
	s_cselect_b32 s4, s8, 0
	v_readfirstlane_b32 s5, v2
	s_add_i32 s4, s5, s4
	s_sext_i32_i16 s8, s4
	s_mul_i32 s4, s4, s7
	s_sub_i32 s4, s9, s4
	s_sext_i32_i16 s4, s4
	s_add_i32 s6, s6, s4
	s_lshr_b32 s7, s6, 3
	s_mul_i32 s7, s7, 6
	s_mov_b32 s4, 0xb459703
	s_mov_b32 s5, 0x155852
	s_lshr_b64 s[4:5], s[4:5], s7
	s_and_b32 s7, s4, 63
	s_add_i32 s8, s8, s7
	s_cmp_gt_i32 s8, 32
	s_cselect_b32 s7, 33, 0
	s_sub_i32 s8, s8, s7

.LBB0_522:
	s_ashr_i32 s7, s7, 3
	s_add_i32 s7, s20, s7
	s_mul_hi_i32 s9, s7, 0x3e0f83e1
	s_lshr_b32 s18, s9, 31
	s_ashr_i32 s9, s9, 6
	s_add_i32 s9, s9, s18
	s_lshl_b32 s19, s9, 3
	s_sub_i32 s18, 0x44, s19
	s_min_i32 s20, s18, 8
	s_abs_i32 s18, s20
	v_cvt_f32_u32_e32 v0, s18
	s_sub_i32 s22, 0, s18
	s_mulk_i32 s9, 0x108
	s_sub_i32 s7, s7, s9
	v_rcp_iflag_f32_e32 v0, v0
	s_abs_i32 s9, s7
	s_xor_b32 s21, s7, s20
	s_ashr_i32 s21, s21, 31
	v_mul_f32_e32 v0, 0x4f7ffffe, v0
	v_cvt_u32_f32_e32 v0, v0
	s_nop 0
	v_readfirstlane_b32 s23, v0
	s_mul_i32 s22, s22, s23
	s_mul_hi_u32 s22, s23, s22
	s_add_i32 s23, s23, s22
	s_mul_hi_u32 s22, s9, s23
	s_mul_i32 s23, s22, s18
	s_sub_i32 s9, s9, s23
	s_add_i32 s24, s22, 1
	s_sub_i32 s23, s9, s18
	s_cmp_ge_u32 s9, s18
	s_cselect_b32 s22, s24, s22
	s_cselect_b32 s9, s23, s9
	s_add_i32 s23, s22, 1
	s_cmp_ge_u32 s9, s18
	s_cselect_b32 s9, s23, s22
	s_xor_b32 s9, s9, s21
	s_sub_i32 s18, s9, s21
	s_mul_i32 s9, s18, s20
	s_sub_i32 s7, s7, s9
	s_add_i32 s20, s19, s7
	s_lshr_b32 s9, s20, 3
	s_mul_i32 s9, s9, 6
	s_mov_b32 s22, 0xb459703
	s_mov_b32 s23, 0x155852
	s_lshr_b64 s[22:23], s[22:23], s9
	s_and_b32 s9, s22, 63
	s_add_i32 s18, s18, s9
	s_cmp_gt_i32 s18, 32
	s_cselect_b32 s9, 33, 0
	s_sub_i32 s18, s18, s9
